# remove dead per-tile K/V voffset VALU from retention S-phase head (use loop-invariant v225)
# baseline (speedup 1.0000x reference)
; #define LAS __attribute__((address_space(3)))
; __device__ __forceinline__ unsigned cvt_pk_bf16(float lo, float hi) { unsigned r; asm volatile("v_cvt_pk_bf16_f32 %0, %1, %2" : "=v"(r) : "v"(lo), "v"(hi)); return r; }
; #define RT_KRD(dst, s0) do { _Pragma("unroll") for (int j_ = 0; j_ < 2; ++j_) dst[j_] = *(const LAS bf16x8*)(kb + ((((2 * ((s0) + j_)) | hh) ^ x15) << 4)); } while (0)
; __device__ __forceinline__ void p2_ret(const Frame& F, ArgsP a, int layer) {
;     ...
;                 { const LAS unsigned char* kb = lds + RT_K0 + bf * 32768 + (32 * wc + kap) * 512;
;     ...
;                   bf16x8 ka[2], kd[2], kc[2];
;                   RT_KRD(ka, 0); RT_KRD(kd, 2); __builtin_amdgcn_sched_barrier(0);
;                   RT_KRD(kc, 4); RT_KMM(ka, 0); if (pre) { RT_DMA_K(kt + 1, bf ^ 1, 0); RT_DMA_V(kt + 1, bf ^ 1, 0); } __builtin_amdgcn_sched_barrier(0);
;                   RT_KRD(ka, 6); RT_KMM(kd, 2); __builtin_amdgcn_sched_barrier(0);
;                   RT_KRD(kd, 8); RT_KMM(kc, 4); if (pre) { RT_DMA_K(kt + 1, bf ^ 1, 1); RT_DMA_V(kt + 1, bf ^ 1, 1); } __builtin_amdgcn_sched_barrier(0);
;                   RT_KRD(kc, 10); RT_KMM(ka, 6); __builtin_amdgcn_sched_barrier(0);
;                   RT_KRD(ka, 12); RT_KMM(kd, 8); if (pre) { RT_DMA_K(kt + 1, bf ^ 1, 2); RT_DMA_V(kt + 1, bf ^ 1, 2); } __builtin_amdgcn_sched_barrier(0);
;                   RT_KRD(kd, 14); RT_KMM(kc, 10); __builtin_amdgcn_sched_barrier(0);
;                   RT_KMM(ka, 12); if (pre) { RT_DMA_K(kt + 1, bf ^ 1, 3); RT_DMA_V(kt + 1, bf ^ 1, 3); } __builtin_amdgcn_sched_barrier(0);
;                   RT_KMM(kd, 14); __builtin_amdgcn_sched_barrier(0);
;     ...
;                 }
;                 { const bool diag = kt >= 2 * qi;
;                   unsigned pk[8];
;                   if (!diag) { const float tf = __builtin_amdgcn_exp2f((float)(128 * (qi - (kt >> 1))) * lg2);
; #pragma unroll
;                       for (int i = 0; i < 8; ++i) pk[i] = cvt_pk_bf16(st[2 * i] * tf, st[2 * i + 1] * tf);
;                   } else { const int lim = wr * 32 + l31 + (2 * qi - kt) * 64 - 32 * wc - 8 * hh;
; #pragma unroll
;                       for (int i = 0; i < 8; ++i) { const int r0 = 2 * i, r1 = 2 * i + 1, o0 = 16 * (r0 >> 3) + (r0 & 7), o1 = 16 * (r1 >> 3) + (r1 & 7);
;                           pk[i] = cvt_pk_bf16((o0 <= lim) ? st[r0] : 0.f, (o1 <= lim) ? st[r1] : 0.f); } }
.LBB0_383:
	v_mov_b32_e32 v0, v207
	s_and_b32 s6, s31, 0x8000
	v_lshlrev_b32_e32 v99, 1, v0
	v_lshrrev_b32_e32 v100, 1, v0
	v_and_b32_e32 v98, 19, v0
	v_and_b32_e32 v99, 8, v99
	v_and_b32_e32 v100, 4, v100
	v_or3_b32 v115, v99, v98, v100
	v_ashrrev_i32_e32 v116, 5, v0
	s_add_i32 s4, s6, 0
	v_or_b32_e32 v98, s80, v115
	v_or_b32_e32 v99, 2, v116
	v_lshl_add_u32 v227, v98, 9, s4
	v_bitop3_b32 v98, v115, v116, 15 bitop3:0x6c
	v_bitop3_b32 v99, v115, v99, 15 bitop3:0x6c
	v_lshl_add_u32 v98, v98, 4, v227
	v_lshl_add_u32 v102, v99, 4, v227
	ds_read_b128 v[98:101], v98
	ds_read_b128 v[190:193], v102
	v_or_b32_e32 v102, 4, v116
	v_bitop3_b32 v102, v115, v102, 15 bitop3:0x6c
	v_or_b32_e32 v103, 6, v116
	v_lshl_add_u32 v102, v102, 4, v227
	v_bitop3_b32 v103, v115, v103, 15 bitop3:0x6c
	v_lshl_add_u32 v103, v103, 4, v227
	ds_read_b128 v[194:197], v102
	ds_read_b128 v[198:201], v103
	v_and_b32_e32 v117, 31, v0
	v_or_b32_e32 v102, 8, v116
	s_xor_b32 s4, s6, 0x8000
	v_bitop3_b32 v102, v115, v102, 15 bitop3:0x6c
	v_or_b32_e32 v103, 10, v116
	s_add_i32 s5, s22, s4
	v_lshl_add_u32 v102, v102, 4, v227
	v_bitop3_b32 v103, v115, v103, 15 bitop3:0x6c
	s_add_i32 s7, s27, 0xfffd0000
	v_lshl_add_u32 v103, v103, 4, v227
	ds_read_b128 v[202:205], v102
	ds_read_b128 v[212:215], v103
	s_add_i32 s7, s25, s30
	s_add_i32 m0, s33, s4
	s_add_i32 s12, s7, 0x80
	s_mov_b32 s46, s42
	s_mov_b32 s47, s43
	buffer_load_dwordx4 v225, s[44:47], s12 offen lds
	s_waitcnt lgkmcnt(5)
	v_mfma_f32_32x32x16_bf16 v[98:113], v[98:101], v[118:121], 0
	s_waitcnt lgkmcnt(4)
	v_mfma_f32_32x32x16_bf16 v[98:113], v[190:193], v[122:125], v[98:113]
	v_or_b32_e32 v190, 12, v116
	v_or_b32_e32 v191, 14, v116
	v_bitop3_b32 v190, v115, v190, 15 bitop3:0x6c
	v_bitop3_b32 v191, v115, v191, 15 bitop3:0x6c
	v_lshl_add_u32 v190, v190, 4, v227
	v_lshl_add_u32 v216, v191, 4, v227
	ds_read_b128 v[190:193], v190
	ds_read_b128 v[216:219], v216
	s_waitcnt lgkmcnt(5)
	v_mfma_f32_32x32x16_bf16 v[98:113], v[194:197], v[126:129], v[98:113]
	v_or_b32_e32 v194, 16, v116
	v_or_b32_e32 v195, 18, v116
	v_bitop3_b32 v194, v115, v194, 15 bitop3:0x6c
	v_bitop3_b32 v195, v115, v195, 15 bitop3:0x6c
	s_add_i32 s4, s4, 0
	v_lshl_add_u32 v194, v194, 4, v227
	s_waitcnt lgkmcnt(4)
	v_mfma_f32_32x32x16_bf16 v[98:113], v[198:201], v[130:133], v[98:113]
	v_lshl_add_u32 v198, v195, 4, v227
	s_add_i32 s12, s27, 0xfffe0000
	s_add_i32 s4, s4, 0x10000
	ds_read_b128 v[194:197], v194
	ds_read_b128 v[198:201], v198
	s_add_i32 m0, s4, s24
	s_add_i32 s12, s7, 0x100080
	buffer_load_dwordx4 v225, s[44:47], s12 offen lds
	s_waitcnt lgkmcnt(5)
	v_mfma_f32_32x32x16_bf16 v[98:113], v[202:205], v[134:137], v[98:113]
	s_waitcnt lgkmcnt(4)
	v_mfma_f32_32x32x16_bf16 v[98:113], v[212:215], v[138:141], v[98:113]
	v_or_b32_e32 v202, 20, v116
	v_or_b32_e32 v203, 22, v116
	v_bitop3_b32 v202, v115, v202, 15 bitop3:0x6c
	v_bitop3_b32 v203, v115, v203, 15 bitop3:0x6c
	v_lshl_add_u32 v202, v202, 4, v227
	v_lshl_add_u32 v212, v203, 4, v227
	ds_read_b128 v[202:205], v202
	ds_read_b128 v[212:215], v212
	s_waitcnt lgkmcnt(5)
	v_mfma_f32_32x32x16_bf16 v[98:113], v[190:193], v[142:145], v[98:113]
	v_or_b32_e32 v190, 24, v116
	v_or_b32_e32 v191, 26, v116
	v_bitop3_b32 v190, v115, v190, 15 bitop3:0x6c
	v_bitop3_b32 v191, v115, v191, 15 bitop3:0x6c
	v_lshl_add_u32 v190, v190, 4, v227
	s_add_i32 s12, s27, 0xffff0000
	s_waitcnt lgkmcnt(4)
	v_mfma_f32_32x32x16_bf16 v[98:113], v[216:219], v[146:149], v[98:113]
	v_lshl_add_u32 v216, v191, 4, v227
	ds_read_b128 v[190:193], v190
	ds_read_b128 v[216:219], v216
	s_add_i32 m0, s4, s26
	s_add_i32 s12, s7, 0x200080
	buffer_load_dwordx4 v225, s[44:47], s12 offen lds
	s_waitcnt lgkmcnt(5)
	v_mfma_f32_32x32x16_bf16 v[98:113], v[194:197], v[150:153], v[98:113]
	s_waitcnt lgkmcnt(4)
	v_mfma_f32_32x32x16_bf16 v[98:113], v[198:201], v[154:157], v[98:113]
	s_waitcnt lgkmcnt(3)
	v_mfma_f32_32x32x16_bf16 v[98:113], v[202:205], v[158:161], v[98:113]
	v_or_b32_e32 v194, 28, v116
	v_or_b32_e32 v195, 30, v116
	v_bitop3_b32 v194, v115, v194, 15 bitop3:0x6c
	v_bitop3_b32 v195, v115, v195, 15 bitop3:0x6c
	v_lshl_add_u32 v194, v194, 4, v227
	v_lshl_add_u32 v198, v195, 4, v227
	ds_read_b128 v[194:197], v194
	ds_read_b128 v[198:201], v198
	s_waitcnt lgkmcnt(4)
	v_mfma_f32_32x32x16_bf16 v[98:113], v[212:215], v[162:165], v[98:113]
	s_add_i32 s7, s7, 0x300080
	s_add_i32 m0, s4, s28
	s_waitcnt lgkmcnt(3)
	v_mfma_f32_32x32x16_bf16 v[98:113], v[190:193], v[166:169], v[98:113]
	buffer_load_dwordx4 v225, s[44:47], s7 offen lds
	s_waitcnt lgkmcnt(2)
	v_mfma_f32_32x32x16_bf16 v[98:113], v[216:219], v[170:173], v[98:113]
	s_waitcnt lgkmcnt(1)
	v_mfma_f32_32x32x16_bf16 v[98:113], v[194:197], v[174:177], v[98:113]
	s_waitcnt lgkmcnt(0)
	v_mfma_f32_32x32x16_bf16 v[98:113], v[198:201], v[178:181], v[98:113]
	v_lshlrev_b32_e32 v250, 3, v115
	v_and_b32_e32 v250, 0x70, v250
	s_add_i32 s13, s64, s6
	v_lshl_add_u32 v251, v115, 7, s13
	v_lshlrev_b32_e32 v252, 4, v116
	s_lshl_b32 s14, s80, 1
	v_xad_u32 v246, v250, v252, v251
	v_add_u32_e32 v253, 32, v252
	v_xad_u32 v247, v250, v253, v251
	v_xor_b32_e32 v246, s14, v246
	v_xor_b32_e32 v247, s14, v247
	v_xor_b32_e32 v248, 64, v246
	v_xor_b32_e32 v249, 64, v247
	ds_read_b128 v[234:237], v246
	ds_read_b128 v[238:241], v247
	s_cmp_ge_u32 s91, s29
	s_mov_b64 s[4:5], -1
	s_cbranch_scc0 .LBB0_385
	v_lshlrev_b32_e32 v190, 3, v116
	v_sub_u32_e32 v117, v117, v190
	v_add_u32_e32 v117, s97, v117
	v_cmp_lt_i32_e32 vcc, -1, v117
	s_mov_b64 s[4:5], 0
	s_nop 3
	v_cndmask_b32_e32 v190, 0, v98, vcc
	v_cmp_lt_i32_e32 vcc, 0, v117
	s_nop 1
	v_cndmask_b32_e32 v191, 0, v99, vcc
	v_cmp_lt_i32_e32 vcc, 1, v117
	v_cvt_pk_bf16_f32 v190, v190, v191
	s_nop 1
	v_cndmask_b32_e32 v191, 0, v100, vcc
	v_cmp_lt_i32_e32 vcc, 2, v117
	s_nop 1
	v_cndmask_b32_e32 v192, 0, v101, vcc
	v_cmp_lt_i32_e32 vcc, 3, v117
	v_cvt_pk_bf16_f32 v191, v191, v192
	s_nop 1
	v_cndmask_b32_e32 v192, 0, v102, vcc
	v_cmp_lt_i32_e32 vcc, 4, v117
	s_nop 1
	v_cndmask_b32_e32 v193, 0, v103, vcc
	v_cmp_lt_i32_e32 vcc, 5, v117
	v_cvt_pk_bf16_f32 v192, v192, v193
	s_nop 1
	v_cndmask_b32_e32 v193, 0, v104, vcc
	v_cmp_lt_i32_e32 vcc, 6, v117
	s_nop 1
	v_cndmask_b32_e32 v194, 0, v105, vcc
	v_cmp_lt_i32_e32 vcc, 15, v117
	v_cvt_pk_bf16_f32 v193, v193, v194
	s_nop 1
	v_cndmask_b32_e32 v194, 0, v106, vcc
	v_cmp_lt_i32_e32 vcc, 16, v117
	s_nop 1
	v_cndmask_b32_e32 v195, 0, v107, vcc
	v_cmp_lt_i32_e32 vcc, 17, v117
	v_cvt_pk_bf16_f32 v194, v194, v195
	s_nop 1
	v_cndmask_b32_e32 v195, 0, v108, vcc
	v_cmp_lt_i32_e32 vcc, 18, v117
	s_nop 1
	v_cndmask_b32_e32 v196, 0, v109, vcc
	v_cmp_lt_i32_e32 vcc, 19, v117
	v_cvt_pk_bf16_f32 v195, v195, v196
	s_nop 1
	v_cndmask_b32_e32 v196, 0, v110, vcc
	v_cmp_lt_i32_e32 vcc, 20, v117
	s_nop 1
	v_cndmask_b32_e32 v197, 0, v111, vcc
	v_cmp_lt_i32_e32 vcc, 21, v117
	v_cvt_pk_bf16_f32 v196, v196, v197
	s_nop 1
	v_cndmask_b32_e32 v197, 0, v112, vcc
	v_cmp_lt_i32_e32 vcc, 22, v117
	s_nop 1
	v_cndmask_b32_e32 v117, 0, v113, vcc
	v_cvt_pk_bf16_f32 v197, v197, v117
